# pair8o plus P6: LayerNorm gain/bias kept in registers across rows (28 of 32 pieces), the per-row reload waits removed
# speedup vs baseline: 1.0078x; 1.0078x over previous
; __device__ __forceinline__ int lane_id() { int l; asm volatile("v_mbcnt_lo_u32_b32 %0, -1, 0\n\tv_mbcnt_hi_u32_b32 %0, -1, %0" : "=v"(l)); return l; }
; __device__ __forceinline__ void p6_final_ln(const Frame& F) {
;     int tid = F.wave * 64 + lane_id(); asm volatile("" : "+v"(tid));
;     const int gw = F.bx * NWAVES + F.wave, NGW = F.G * NWAVES, lane = tid & 63;
;     for (int m = gw; m < M; m += NGW) {
;         const float* xr = (m < SEQ) ? F.xp + (size_t)m * DM : F.xs + (size_t)(m - SEQ) * DM;
;         const bf16_t* orow = F.OUTB + (size_t)m * DM;
;         f32x4 z[16]; float s = 0.f;
; #pragma unroll
;         for (int j = 0; j < 8; ++j) { const int col = j * 512 + lane * 8;
;             const f32x4 xa = *(const f32x4*)(xr + col), xb = *(const f32x4*)(xr + col + 4); const u32x4 o = *(const u32x4*)(orow + col);
;             z[2 * j]     = xa * DN_ALPHA + (f32x4){bflo(o.x), bfhi(o.x), bflo(o.y), bfhi(o.y)};
;             z[2 * j + 1] = xb * DN_ALPHA + (f32x4){bflo(o.z), bfhi(o.z), bflo(o.w), bfhi(o.w)};
;             s += (z[2 * j][0] + z[2 * j][1]) + (z[2 * j][2] + z[2 * j][3]) + (z[2 * j + 1][0] + z[2 * j + 1][1]) + (z[2 * j + 1][2] + z[2 * j + 1][3]); }
;         const float mean = wave_sum(s) * (1.f / DM); float q = 0.f;
; #pragma unroll
;         for (int j = 0; j < 16; ++j) { const f32x4 d = z[j] - mean; z[j] = d; q += (d[0] * d[0] + d[1] * d[1]) + (d[2] * d[2] + d[3] * d[3]); }
;         const float rstd = __builtin_amdgcn_rsqf(wave_sum(q) * (1.f / DM) + LN_EPS);
;         float* yr = F.out + (size_t)m * DM;
; #pragma unroll
;         for (int j = 0; j < 8; ++j) { const int col = j * 512 + lane * 8;
;             const f32x4 ga = *(const f32x4*)(F.ln_g + col), gb = *(const f32x4*)(F.ln_g + col + 4), ba = *(const f32x4*)(F.ln_b + col), bb = *(const f32x4*)(F.ln_b + col + 4);
.LBB0_572:
	s_cmp_lt_i32 s42, 7
	s_cselect_b64 s[0:1], -1, 0
	s_and_b64 s[0:1], s[0:1], s[4:5]
	s_andn2_b64 vcc, exec, s[0:1]
	s_cbranch_vccnz .LBB0_578
	s_lshl_b32 s0, s2, 3
	v_mbcnt_lo_u32_b32 v0, -1, 0
	v_mbcnt_hi_u32_b32 v0, -1, v0
	s_add_i32 s0, s97, s0
	v_add_u32_e32 v0, s74, v0
	s_cmpk_gt_i32 s0, 0x5fff
	s_cbranch_scc1 .LBB0_578
	v_lshlrev_b32_e32 v0, 3, v0
	v_and_b32_e32 v4, 0x1f8, v0
	v_mbcnt_lo_u32_b32 v0, -1, 0
	v_mbcnt_hi_u32_b32 v0, -1, v0
	v_and_b32_e32 v1, 64, v0
	v_add_u32_e32 v1, 64, v1
	v_xor_b32_e32 v2, 1, v0
	v_cmp_lt_i32_e32 vcc, v2, v1
	v_readlane_b32 s16, v255, 0
	v_readlane_b32 s22, v255, 6
	v_cndmask_b32_e32 v2, v0, v2, vcc
	v_lshlrev_b32_e32 v5, 2, v2
	v_xor_b32_e32 v2, 2, v0
	v_cmp_lt_i32_e32 vcc, v2, v1
	v_readlane_b32 s23, v255, 7
	s_mov_b64 s[6:7], s[22:23]
	v_cndmask_b32_e32 v2, v0, v2, vcc
	v_lshlrev_b32_e32 v7, 2, v2
	v_xor_b32_e32 v2, 4, v0
	v_cmp_lt_i32_e32 vcc, v2, v1
	v_or_b32_e32 v42, 0x600, v4
	v_or_b32_e32 v6, 0x800, v4
	v_cndmask_b32_e32 v2, v0, v2, vcc
	v_lshlrev_b32_e32 v9, 2, v2
	v_xor_b32_e32 v2, 8, v0
	v_cmp_lt_i32_e32 vcc, v2, v1
	v_or_b32_e32 v8, 0xa00, v4
	v_or_b32_e32 v10, 0xc00, v4
	v_cndmask_b32_e32 v2, v0, v2, vcc
	v_lshlrev_b32_e32 v11, 2, v2
	v_xor_b32_e32 v2, 16, v0
	v_cmp_lt_i32_e32 vcc, v2, v1
	v_or_b32_e32 v12, 0xe00, v4
	s_lshl_b32 s2, s34, 3
	v_cndmask_b32_e32 v2, v0, v2, vcc
	v_lshlrev_b32_e32 v13, 2, v2
	v_xor_b32_e32 v2, 32, v0
	v_cmp_lt_i32_e32 vcc, v2, v1
	v_mov_b32_e32 v1, 0
	s_ashr_i32 s1, s0, 31
	v_cndmask_b32_e32 v0, v0, v2, vcc
	v_lshlrev_b32_e32 v103, 2, v0
	v_or_b32_e32 v2, 0x400, v4
	v_lshlrev_b32_e32 v0, 2, v4
	v_lshl_add_u64 v[14:15], s[6:7], 0, v[0:1]
	v_lshl_add_u64 v[16:17], s[36:37], 0, v[0:1]
	v_lshlrev_b32_e32 v0, 2, v2
	v_lshl_add_u64 v[18:19], s[6:7], 0, v[0:1]
	v_lshl_add_u64 v[20:21], s[36:37], 0, v[0:1]
	v_lshlrev_b32_e32 v0, 2, v42
	v_lshl_add_u64 v[22:23], s[6:7], 0, v[0:1]
	v_lshl_add_u64 v[24:25], s[36:37], 0, v[0:1]
	v_lshlrev_b32_e32 v0, 2, v6
	v_lshl_add_u64 v[26:27], s[6:7], 0, v[0:1]
	v_lshl_add_u64 v[28:29], s[36:37], 0, v[0:1]
	v_lshlrev_b32_e32 v0, 2, v8
	v_lshl_add_u64 v[30:31], s[6:7], 0, v[0:1]
	v_lshl_add_u64 v[32:33], s[36:37], 0, v[0:1]
	v_lshlrev_b32_e32 v0, 2, v10
	v_lshl_add_u64 v[34:35], s[6:7], 0, v[0:1]
	v_lshl_add_u64 v[36:37], s[36:37], 0, v[0:1]
	v_lshlrev_b32_e32 v0, 2, v12
	v_lshl_add_u64 v[38:39], s[6:7], 0, v[0:1]
	s_ashr_i32 s3, s2, 31
	s_lshl_b64 s[6:7], s[0:1], 14
	s_add_u32 s6, s12, s6
	s_mov_b32 s5, 0
	v_lshl_add_u64 v[40:41], s[36:37], 0, v[0:1]
	s_addc_u32 s7, s13, s7
	s_lshl_b64 s[8:9], s[2:3], 14
	s_mov_b32 s10, 0x3f9837f0
	v_lshlrev_b32_e32 v104, 2, v2
	v_lshlrev_b32_e32 v105, 2, v42
	v_mov_b32_e32 v106, 0x3727c5ac
	v_readlane_b32 s17, v255, 1
	v_readlane_b32 s18, v255, 2
	v_readlane_b32 s19, v255, 3
	v_readlane_b32 s20, v255, 4
	v_readlane_b32 s21, v255, 5
	global_load_dwordx4 v[140:143], v[14:15], off offset:16
	global_load_dwordx4 v[144:147], v[14:15], off
	global_load_dwordx4 v[148:151], v[16:17], off offset:16
	global_load_dwordx4 v[152:155], v[16:17], off
	global_load_dwordx4 v[156:159], v[16:17], off offset:2048
	global_load_dwordx4 v[160:163], v[14:15], off offset:2048
	global_load_dwordx4 v[164:167], v[14:15], off offset:2064
	global_load_dwordx4 v[168:171], v[16:17], off offset:2064
	global_load_dwordx4 v[172:175], v[20:21], off
	global_load_dwordx4 v[176:179], v[18:19], off
	global_load_dwordx4 v[180:183], v[18:19], off offset:16
	global_load_dwordx4 v[184:187], v[20:21], off offset:16
	global_load_dwordx4 v[188:191], v[24:25], off
	global_load_dwordx4 v[192:195], v[22:23], off
	global_load_dwordx4 v[196:199], v[22:23], off offset:16
	global_load_dwordx4 v[200:203], v[24:25], off offset:16
	global_load_dwordx4 v[204:207], v[28:29], off
	global_load_dwordx4 v[208:211], v[26:27], off
	global_load_dwordx4 v[212:215], v[26:27], off offset:16
	global_load_dwordx4 v[216:219], v[28:29], off offset:16
	global_load_dwordx4 v[220:223], v[32:33], off
	global_load_dwordx4 v[224:227], v[30:31], off
	global_load_dwordx4 v[228:231], v[30:31], off offset:16
	global_load_dwordx4 v[232:235], v[32:33], off offset:16
	global_load_dwordx4 v[236:239], v[36:37], off
	global_load_dwordx4 v[240:243], v[34:35], off
	global_load_dwordx4 v[244:247], v[34:35], off offset:16
	global_load_dwordx4 v[248:251], v[36:37], off offset:16
	s_waitcnt vmcnt(0)
	s_branch .LBB0_576
; __device__ __forceinline__ void p6_final_ln(const Frame& F) {
;     ...
;     for (int m = gw; m < M; m += NGW) {
;         const float* xr = (m < SEQ) ? F.xp + (size_t)m * DM : F.xs + (size_t)(m - SEQ) * DM;
;         const bf16_t* orow = F.OUTB + (size_t)m * DM;
;         f32x4 z[16]; float s = 0.f;
; #pragma unroll
;         for (int j = 0; j < 8; ++j) { const int col = j * 512 + lane * 8;
;             const f32x4 xa = *(const f32x4*)(xr + col), xb = *(const f32x4*)(xr + col + 4); const u32x4 o = *(const u32x4*)(orow + col);
;             z[2 * j]     = xa * DN_ALPHA + (f32x4){bflo(o.x), bfhi(o.x), bflo(o.y), bfhi(o.y)};
;             z[2 * j + 1] = xb * DN_ALPHA + (f32x4){bflo(o.z), bfhi(o.z), bflo(o.w), bfhi(o.w)};
;             s += (z[2 * j][0] + z[2 * j][1]) + (z[2 * j][2] + z[2 * j][3]) + (z[2 * j + 1][0] + z[2 * j + 1][1]) + (z[2 * j + 1][2] + z[2 * j + 1][3]); }
.LBB0_575:
	s_lshl_b64 s[18:19], s[12:13], 13
	s_add_u32 s18, s26, s18
	s_addc_u32 s19, s27, s19
	v_lshlrev_b32_e32 v70, 1, v4
	global_load_dwordx4 v[42:45], v70, s[18:19]
	global_load_dwordx4 v[46:49], v70, s[18:19] offset:1024
	global_load_dwordx4 v[50:53], v70, s[18:19] offset:2048
	v_lshlrev_b32_e32 v109, 2, v4
	global_load_dwordx4 v[54:57], v109, s[16:17]
	global_load_dwordx4 v[58:61], v109, s[16:17] offset:16
	global_load_dwordx4 v[62:65], v109, s[16:17] offset:2048
	global_load_dwordx4 v[66:69], v109, s[16:17] offset:2064
	global_load_dwordx4 v[74:77], v104, s[16:17]
	global_load_dwordx4 v[78:81], v104, s[16:17] offset:16
	global_load_dwordx4 v[0:3], v105, s[16:17] offset:16
	global_load_dwordx4 v[82:85], v105, s[16:17]
	v_lshlrev_b32_e32 v107, 2, v6
	v_lshlrev_b32_e32 v71, 1, v6
	v_lshlrev_b32_e32 v108, 2, v8
	v_lshlrev_b32_e32 v72, 1, v8
	global_load_dwordx4 v[86:89], v107, s[16:17] offset:16
	global_load_dwordx4 v[94:97], v107, s[16:17]
	global_load_dwordx4 v[112:115], v108, s[16:17] offset:16
	global_load_dwordx4 v[116:119], v108, s[16:17]
	global_load_dwordx4 v[98:101], v70, s[18:19] offset:3072
	global_load_dwordx4 v[120:123], v71, s[18:19]
	global_load_dwordx4 v[124:127], v72, s[18:19]
	s_lshl_b64 s[12:13], s[12:13], 14
	s_add_u32 s12, s38, s12
	s_addc_u32 s13, s39, s13
	s_add_u32 s0, s0, s2
	s_addc_u32 s1, s1, s3
	s_add_u32 s6, s6, s8
	s_addc_u32 s7, s7, s9
	s_cmpk_lt_i32 s0, 0x6000
	s_barrier
	s_waitcnt vmcnt(17)
	v_lshlrev_b32_e32 v70, 16, v42
	v_and_b32_e32 v71, 0xffff0000, v42
	v_lshlrev_b32_e32 v42, 16, v43
	v_and_b32_e32 v43, 0xffff0000, v43
	v_lshlrev_b32_e32 v72, 16, v44
	v_and_b32_e32 v73, 0xffff0000, v44
	v_lshlrev_b32_e32 v44, 16, v45
	v_and_b32_e32 v45, 0xffff0000, v45
	s_waitcnt vmcnt(16)
	v_lshlrev_b32_e32 v110, 16, v46
	v_and_b32_e32 v111, 0xffff0000, v46
	v_lshlrev_b32_e32 v46, 16, v47
	v_and_b32_e32 v47, 0xffff0000, v47
	v_lshlrev_b32_e32 v128, 16, v48
	v_and_b32_e32 v129, 0xffff0000, v48
	v_lshlrev_b32_e32 v48, 16, v49
	v_and_b32_e32 v49, 0xffff0000, v49
	s_waitcnt vmcnt(14)
	v_pk_fma_f32 v[90:91], v[56:57], s[10:11], v[42:43] op_sel_hi:[1,0,1]
	v_pk_fma_f32 v[92:93], v[54:55], s[10:11], v[70:71] op_sel_hi:[1,0,1]
	s_waitcnt vmcnt(13)
	v_pk_fma_f32 v[70:71], v[60:61], s[10:11], v[44:45] op_sel_hi:[1,0,1]
	v_pk_fma_f32 v[72:73], v[58:59], s[10:11], v[72:73] op_sel_hi:[1,0,1]
	s_waitcnt vmcnt(12)
	v_pk_fma_f32 v[60:61], v[64:65], s[10:11], v[46:47] op_sel_hi:[1,0,1]
	v_pk_fma_f32 v[58:59], v[62:63], s[10:11], v[110:111] op_sel_hi:[1,0,1]
	s_waitcnt vmcnt(11)
	v_pk_fma_f32 v[56:57], v[68:69], s[10:11], v[48:49] op_sel_hi:[1,0,1]
	v_pk_fma_f32 v[54:55], v[66:67], s[10:11], v[128:129] op_sel_hi:[1,0,1]
	v_mov_b32_e32 v46, v92
	v_mov_b32_e32 v47, v58
	v_mov_b32_e32 v48, v93
	v_mov_b32_e32 v49, v59
	v_mov_b32_e32 v62, v90
	v_mov_b32_e32 v63, v60
	v_mov_b32_e32 v64, v91
	v_mov_b32_e32 v65, v61
	v_lshlrev_b32_e32 v130, 16, v50
	v_and_b32_e32 v131, 0xffff0000, v50
	v_lshlrev_b32_e32 v50, 16, v51
	v_and_b32_e32 v51, 0xffff0000, v51
	v_mov_b32_e32 v66, v72
	v_mov_b32_e32 v67, v54
	v_mov_b32_e32 v68, v73
	v_mov_b32_e32 v69, v55
	v_pk_add_f32 v[46:47], v[46:47], v[48:49]
	v_pk_add_f32 v[48:49], v[62:63], v[64:65]
	v_lshlrev_b32_e32 v132, 16, v52
	v_and_b32_e32 v133, 0xffff0000, v52
	v_lshlrev_b32_e32 v134, 16, v53
	v_and_b32_e32 v135, 0xffff0000, v53
	s_waitcnt vmcnt(10)
	v_pk_fma_f32 v[52:53], v[76:77], s[10:11], v[50:51] op_sel_hi:[1,0,1]
	v_pk_fma_f32 v[50:51], v[74:75], s[10:11], v[130:131] op_sel_hi:[1,0,1]
	v_mov_b32_e32 v74, v70
	v_mov_b32_e32 v75, v56
	v_mov_b32_e32 v76, v71
	v_mov_b32_e32 v77, v57
	v_pk_add_f32 v[62:63], v[66:67], v[68:69]
	v_pk_add_f32 v[46:47], v[46:47], v[48:49]
	v_pk_add_f32 v[64:65], v[74:75], v[76:77]
	v_pk_add_f32 v[46:47], v[62:63], v[46:47]
	s_waitcnt vmcnt(9)
	v_pk_fma_f32 v[44:45], v[80:81], s[10:11], v[134:135] op_sel_hi:[1,0,1]
	v_pk_fma_f32 v[42:43], v[78:79], s[10:11], v[132:133] op_sel_hi:[1,0,1]
	v_pk_mov_b32 v[78:79], v[50:51], v[52:53] op_sel:[1,0]
	v_mov_b32_e32 v80, v50
	v_mov_b32_e32 v81, v53
	v_pk_add_f32 v[46:47], v[64:65], v[46:47]
	v_pk_add_f32 v[66:67], v[78:79], v[80:81]
	v_add_f32_e32 v46, 0, v46
	v_mov_b32_e32 v48, v44
	v_mov_b32_e32 v49, v42
	v_mov_b32_e32 v62, v45
	v_mov_b32_e32 v63, v43
	v_add_f32_e32 v76, v46, v47
	v_pk_add_f32 v[46:47], v[66:67], v[66:67] op_sel:[0,1] op_sel_hi:[1,0]
	v_pk_add_f32 v[62:63], v[48:49], v[62:63]
	v_lshlrev_b32_e32 v111, 2, v10
	v_pk_add_f32 v[64:65], v[62:63], v[46:47] op_sel:[1,0] op_sel_hi:[0,1]
	v_lshlrev_b32_e32 v46, 1, v10
	global_load_dwordx4 v[46:49], v46, s[18:19]
	v_pk_add_f32 v[78:79], v[62:63], v[64:65]
	global_load_dwordx4 v[62:65], v111, s[16:17] offset:16
	global_load_dwordx4 v[66:69], v111, s[16:17]
	v_lshlrev_b32_e32 v77, 1, v12
	global_load_dwordx4 v[128:131], v77, s[18:19]
	v_lshlrev_b32_e32 v110, 2, v12
	global_load_dwordx4 v[132:135], v110, s[16:17] offset:16
	global_load_dwordx4 v[136:139], v110, s[16:17]
	s_waitcnt vmcnt(8)
	v_lshlrev_b32_e32 v74, 16, v98
	v_and_b32_e32 v75, 0xffff0000, v98
	v_lshlrev_b32_e32 v80, 16, v99
	v_and_b32_e32 v81, 0xffff0000, v99
	v_pk_fma_f32 v[80:81], v[84:85], s[10:11], v[80:81] op_sel_hi:[1,0,1]
	v_pk_fma_f32 v[74:75], v[82:83], s[10:11], v[74:75] op_sel_hi:[1,0,1]
	v_lshlrev_b32_e32 v82, 16, v100
	v_and_b32_e32 v83, 0xffff0000, v100
	v_lshlrev_b32_e32 v84, 16, v101
	v_and_b32_e32 v85, 0xffff0000, v101
	v_pk_fma_f32 v[100:101], v[2:3], s[10:11], v[84:85] op_sel_hi:[1,0,1]
	v_pk_fma_f32 v[98:99], v[0:1], s[10:11], v[82:83] op_sel_hi:[1,0,1]
	s_waitcnt vmcnt(7)
; __device__ __forceinline__ float wave_sum(float v) {
; #pragma unroll
;     for (int o = 1; o < 64; o <<= 1) v += __shfl_xor(v, o);
;     return v;
; __device__ __forceinline__ void p6_final_ln(const Frame& F) {
;     ...
;         for (int j = 0; j < 8; ++j) { const int col = j * 512 + lane * 8;
;             const f32x4 xa = *(const f32x4*)(xr + col), xb = *(const f32x4*)(xr + col + 4); const u32x4 o = *(const u32x4*)(orow + col);
;             z[2 * j]     = xa * DN_ALPHA + (f32x4){bflo(o.x), bfhi(o.x), bflo(o.y), bfhi(o.y)};
;             z[2 * j + 1] = xb * DN_ALPHA + (f32x4){bflo(o.z), bfhi(o.z), bflo(o.w), bfhi(o.w)};
;             s += (z[2 * j][0] + z[2 * j][1]) + (z[2 * j][2] + z[2 * j][3]) + (z[2 * j + 1][0] + z[2 * j + 1][1]) + (z[2 * j + 1][2] + z[2 * j + 1][3]); }
;         const float mean = wave_sum(s) * (1.f / DM); float q = 0.f;
	v_lshlrev_b32_e32 v82, 16, v120
	v_and_b32_e32 v83, 0xffff0000, v120
	v_lshlrev_b32_e32 v84, 16, v121
	v_and_b32_e32 v85, 0xffff0000, v121
	v_pk_fma_f32 v[96:97], v[96:97], s[10:11], v[84:85] op_sel_hi:[1,0,1]
	v_pk_fma_f32 v[94:95], v[94:95], s[10:11], v[82:83] op_sel_hi:[1,0,1]
	v_lshlrev_b32_e32 v82, 16, v122
	v_and_b32_e32 v83, 0xffff0000, v122
	v_lshlrev_b32_e32 v84, 16, v123
	v_and_b32_e32 v85, 0xffff0000, v123
	v_add_f32_e32 v0, v74, v75
	v_add_f32_e32 v2, v80, v81
	v_pk_fma_f32 v[84:85], v[88:89], s[10:11], v[84:85] op_sel_hi:[1,0,1]
	v_pk_fma_f32 v[82:83], v[86:87], s[10:11], v[82:83] op_sel_hi:[1,0,1]
	v_mov_b32_e32 v86, v98
	v_mov_b32_e32 v87, v94
	v_mov_b32_e32 v88, v99
	v_mov_b32_e32 v89, v95
	v_mov_b32_e32 v1, v96
	v_mov_b32_e32 v3, v97
	v_pk_add_f32 v[86:87], v[86:87], v[88:89]
	v_pk_add_f32 v[0:1], v[0:1], v[2:3]
	v_mov_b32_e32 v2, v100
	v_pk_add_f32 v[0:1], v[86:87], v[0:1]
	v_mov_b32_e32 v3, v82
	v_mov_b32_e32 v86, v101
	v_mov_b32_e32 v87, v83
	v_pk_add_f32 v[2:3], v[2:3], v[86:87]
	v_mov_b32_e32 v77, v84
	v_mov_b32_e32 v79, v85
	v_pk_add_f32 v[0:1], v[2:3], v[0:1]
	v_pk_add_f32 v[2:3], v[76:77], v[78:79]
	s_nop 0
	v_pk_add_f32 v[0:1], v[2:3], v[0:1]
	s_waitcnt vmcnt(6)
	v_lshlrev_b32_e32 v2, 16, v125
	v_pk_add_f32 v[120:121], v[0:1], v[0:1] op_sel:[0,1] op_sel_hi:[1,0]
	v_lshlrev_b32_e32 v0, 16, v124
	v_and_b32_e32 v1, 0xffff0000, v124
	v_and_b32_e32 v3, 0xffff0000, v125
	v_pk_fma_f32 v[88:89], v[118:119], s[10:11], v[2:3] op_sel_hi:[1,0,1]
	v_pk_fma_f32 v[86:87], v[116:117], s[10:11], v[0:1] op_sel_hi:[1,0,1]
	v_lshlrev_b32_e32 v0, 16, v126
	v_and_b32_e32 v1, 0xffff0000, v126
	v_lshlrev_b32_e32 v2, 16, v127
	v_and_b32_e32 v3, 0xffff0000, v127
	v_pk_fma_f32 v[78:79], v[114:115], s[10:11], v[2:3] op_sel_hi:[1,0,1]
	v_pk_fma_f32 v[76:77], v[112:113], s[10:11], v[0:1] op_sel_hi:[1,0,1]
	v_pk_mov_b32 v[0:1], v[86:87], v[88:89] op_sel:[1,0]
	v_mov_b32_e32 v2, v86
	v_mov_b32_e32 v3, v89
	v_pk_add_f32 v[0:1], v[0:1], v[2:3]
	v_mov_b32_e32 v2, v78
	v_mov_b32_e32 v3, v76
	v_mov_b32_e32 v112, v79
	v_mov_b32_e32 v113, v77
	v_pk_add_f32 v[0:1], v[0:1], v[0:1] op_sel:[0,1] op_sel_hi:[1,0]
	v_pk_add_f32 v[2:3], v[2:3], v[112:113]
	s_nop 0
	v_pk_add_f32 v[0:1], v[2:3], v[0:1] op_sel:[1,0] op_sel_hi:[0,1]
	v_pk_add_f32 v[112:113], v[2:3], v[0:1]
	s_waitcnt vmcnt(5)
	v_lshlrev_b32_e32 v0, 16, v46
	v_and_b32_e32 v1, 0xffff0000, v46
	v_lshlrev_b32_e32 v2, 16, v47
	v_and_b32_e32 v3, 0xffff0000, v47
	s_waitcnt vmcnt(3)
	v_pk_fma_f32 v[68:69], v[68:69], s[10:11], v[2:3] op_sel_hi:[1,0,1]
	v_pk_fma_f32 v[66:67], v[66:67], s[10:11], v[0:1] op_sel_hi:[1,0,1]
	v_lshlrev_b32_e32 v0, 16, v48
	v_and_b32_e32 v1, 0xffff0000, v48
	v_lshlrev_b32_e32 v2, 16, v49
	v_and_b32_e32 v3, 0xffff0000, v49
	v_pk_fma_f32 v[64:65], v[64:65], s[10:11], v[2:3] op_sel_hi:[1,0,1]
	v_pk_fma_f32 v[62:63], v[62:63], s[10:11], v[0:1] op_sel_hi:[1,0,1]
	s_waitcnt vmcnt(2)
	v_lshlrev_b32_e32 v2, 16, v128
	v_and_b32_e32 v3, 0xffff0000, v128
	v_lshlrev_b32_e32 v0, 16, v129
	v_and_b32_e32 v1, 0xffff0000, v129
	s_waitcnt vmcnt(0)
	v_pk_fma_f32 v[0:1], v[138:139], s[10:11], v[0:1] op_sel_hi:[1,0,1]
	v_pk_fma_f32 v[2:3], v[136:137], s[10:11], v[2:3] op_sel_hi:[1,0,1]
	v_add_f32_e32 v114, v66, v67
	v_add_f32_e32 v116, v68, v69
	v_lshlrev_b32_e32 v48, 16, v130
	v_and_b32_e32 v49, 0xffff0000, v130
	v_mov_b32_e32 v118, v62
	v_mov_b32_e32 v119, v2
	v_mov_b32_e32 v122, v63
	v_mov_b32_e32 v123, v3
	v_mov_b32_e32 v115, v0
	v_mov_b32_e32 v117, v1
	v_lshlrev_b32_e32 v46, 16, v131
	v_and_b32_e32 v47, 0xffff0000, v131
	v_pk_fma_f32 v[48:49], v[132:133], s[10:11], v[48:49] op_sel_hi:[1,0,1]
	v_pk_add_f32 v[118:119], v[118:119], v[122:123]
	v_pk_add_f32 v[114:115], v[114:115], v[116:117]
	v_pk_fma_f32 v[46:47], v[134:135], s[10:11], v[46:47] op_sel_hi:[1,0,1]
	v_pk_add_f32 v[114:115], v[118:119], v[114:115]
	v_mov_b32_e32 v116, v64
	v_mov_b32_e32 v117, v48
	v_mov_b32_e32 v118, v65
	v_mov_b32_e32 v119, v49
	v_pk_add_f32 v[116:117], v[116:117], v[118:119]
	v_mov_b32_e32 v121, v46
	v_mov_b32_e32 v113, v47
	v_pk_add_f32 v[114:115], v[116:117], v[114:115]
	v_pk_add_f32 v[112:113], v[120:121], v[112:113]
	s_nop 0
	v_pk_add_f32 v[112:113], v[112:113], v[114:115]
	s_nop 0
	v_add_f32_e32 v102, v112, v113
	ds_bpermute_b32 v112, v5, v102
	s_waitcnt lgkmcnt(0)
	v_add_f32_e32 v102, v102, v112
	ds_bpermute_b32 v112, v7, v102
	s_waitcnt lgkmcnt(0)
	v_add_f32_e32 v102, v102, v112
	ds_bpermute_b32 v112, v9, v102
	s_waitcnt lgkmcnt(0)
	v_add_f32_e32 v102, v102, v112
	ds_bpermute_b32 v112, v11, v102
	s_waitcnt lgkmcnt(0)
	v_add_f32_e32 v102, v102, v112
	ds_bpermute_b32 v112, v13, v102
	s_waitcnt lgkmcnt(0)
	v_add_f32_e32 v102, v102, v112
	ds_bpermute_b32 v112, v103, v102
	s_waitcnt lgkmcnt(0)
; __device__ __forceinline__ void p6_final_ln(const Frame& F) {
;     ...
;         const float mean = wave_sum(s) * (1.f / DM); float q = 0.f;
; #pragma unroll
;         for (int j = 0; j < 16; ++j) { const f32x4 d = z[j] - mean; z[j] = d; q += (d[0] * d[0] + d[1] * d[1]) + (d[2] * d[2] + d[3] * d[3]); }
;         const float rstd = __builtin_amdgcn_rsqf(wave_sum(q) * (1.f / DM) + LN_EPS);
;         float* yr = F.out + (size_t)m * DM;
; #pragma unroll
;         for (int j = 0; j < 8; ++j) { const int col = j * 512 + lane * 8;
;             const f32x4 ga = *(const f32x4*)(F.ln_g + col), gb = *(const f32x4*)(F.ln_g + col + 4), ba = *(const f32x4*)(F.ln_b + col), bb = *(const f32x4*)(F.ln_b + col + 4);
	v_add_f32_e32 v136, v102, v112
	v_fmamk_f32 v93, v136, 0xb9800000, v93
	v_fmac_f32_e32 v92, 0xb9800000, v136
	v_fmamk_f32 v91, v136, 0xb9800000, v91
	v_fmac_f32_e32 v90, 0xb9800000, v136
	v_pk_mul_f32 v[112:113], v[90:91], v[90:91]
	v_pk_mul_f32 v[114:115], v[92:93], v[92:93]
	v_fmamk_f32 v73, v136, 0xb9800000, v73
	v_pk_mov_b32 v[116:117], v[114:115], v[112:113] op_sel:[1,0]
	v_mov_b32_e32 v115, v113
	v_fmac_f32_e32 v72, 0xb9800000, v136
	v_fmamk_f32 v71, v136, 0xb9800000, v71
	v_fmac_f32_e32 v70, 0xb9800000, v136
	v_pk_add_f32 v[112:113], v[116:117], v[114:115]
	v_pk_mul_f32 v[114:115], v[70:71], v[70:71]
	v_pk_mul_f32 v[116:117], v[72:73], v[72:73]
	v_fmac_f32_e32 v58, 0xb9800000, v136
	v_pk_mov_b32 v[118:119], v[116:117], v[114:115] op_sel:[1,0]
	v_mov_b32_e32 v117, v115
	v_fmamk_f32 v59, v136, 0xb9800000, v59
	v_fmac_f32_e32 v60, 0xb9800000, v136
	v_mul_f32_e32 v102, v58, v58
	v_pk_add_f32 v[114:115], v[118:119], v[116:117]
	v_fmamk_f32 v61, v136, 0xb9800000, v61
	v_pk_fma_f32 v[116:117], v[58:59], v[58:59], v[102:103] op_sel_hi:[1,1,0]
	v_mul_f32_e32 v102, v60, v60
	v_pk_add_f32 v[112:113], v[112:113], v[112:113] op_sel_hi:[0,1]
	v_pk_add_f32 v[114:115], v[114:115], v[114:115] op_sel_hi:[0,1]
	v_pk_fma_f32 v[118:119], v[60:61], v[60:61], v[102:103] op_sel_hi:[1,1,0]
	v_fmamk_f32 v57, v136, 0xb9800000, v57
	v_fmac_f32_e32 v56, 0xb9800000, v136
	v_fmamk_f32 v55, v136, 0xb9800000, v55
	v_fmac_f32_e32 v54, 0xb9800000, v136
	v_mul_f32_e32 v116, v54, v54
	v_mul_f32_e32 v118, v55, v55
	v_mul_f32_e32 v112, v56, v56
	v_mul_f32_e32 v114, v57, v57
	v_pk_add_f32 v[116:117], v[116:117], v[118:119]
	v_pk_add_f32 v[112:113], v[112:113], v[114:115]
	v_fmamk_f32 v51, v136, 0xb9800000, v51
	v_fmac_f32_e32 v50, 0xb9800000, v136
	v_fmamk_f32 v53, v136, 0xb9800000, v53
	v_fmac_f32_e32 v52, 0xb9800000, v136
	v_pk_add_f32 v[112:113], v[116:117], v[112:113]
	v_pk_mul_f32 v[114:115], v[52:53], v[52:53]
	v_pk_mul_f32 v[116:117], v[50:51], v[50:51]
	v_fmac_f32_e32 v42, 0xb9800000, v136
	v_pk_mov_b32 v[118:119], v[116:117], v[114:115] op_sel:[1,0]
	v_mov_b32_e32 v117, v115
	v_fmamk_f32 v43, v136, 0xb9800000, v43
	v_fmac_f32_e32 v44, 0xb9800000, v136
	v_mul_f32_e32 v102, v42, v42
	v_pk_add_f32 v[114:115], v[118:119], v[116:117]
	v_fmamk_f32 v45, v136, 0xb9800000, v45
	v_pk_fma_f32 v[116:117], v[42:43], v[42:43], v[102:103] op_sel_hi:[1,1,0]
	v_mul_f32_e32 v102, v44, v44
	v_pk_add_f32 v[112:113], v[112:113], v[112:113] op_sel_hi:[0,1]
	v_pk_add_f32 v[114:115], v[114:115], v[114:115] op_sel_hi:[0,1]
	v_pk_fma_f32 v[118:119], v[44:45], v[44:45], v[102:103] op_sel_hi:[1,1,0]
	v_fmamk_f32 v81, v136, 0xb9800000, v81
	v_fmac_f32_e32 v80, 0xb9800000, v136
	v_fmamk_f32 v75, v136, 0xb9800000, v75
	v_fmac_f32_e32 v74, 0xb9800000, v136
	v_mul_f32_e32 v116, v74, v74
	v_mul_f32_e32 v118, v75, v75
	v_mul_f32_e32 v114, v80, v80
	v_mul_f32_e32 v112, v81, v81
	v_pk_add_f32 v[116:117], v[116:117], v[118:119]
	v_pk_add_f32 v[112:113], v[114:115], v[112:113]
	v_fmamk_f32 v99, v136, 0xb9800000, v99
	v_fmac_f32_e32 v98, 0xb9800000, v136
	v_fmamk_f32 v101, v136, 0xb9800000, v101
	v_fmac_f32_e32 v100, 0xb9800000, v136
	v_pk_add_f32 v[112:113], v[116:117], v[112:113]
	v_pk_mul_f32 v[114:115], v[100:101], v[100:101]
	v_pk_mul_f32 v[116:117], v[98:99], v[98:99]
	v_fmac_f32_e32 v94, 0xb9800000, v136
	v_pk_mov_b32 v[118:119], v[116:117], v[114:115] op_sel:[1,0]
	v_mov_b32_e32 v117, v115
	v_fmamk_f32 v95, v136, 0xb9800000, v95
	v_fmac_f32_e32 v96, 0xb9800000, v136
	v_mul_f32_e32 v102, v94, v94
	v_pk_add_f32 v[114:115], v[118:119], v[116:117]
	v_fmamk_f32 v97, v136, 0xb9800000, v97
	v_pk_fma_f32 v[116:117], v[94:95], v[94:95], v[102:103] op_sel_hi:[1,1,0]
	v_mul_f32_e32 v102, v96, v96
	v_pk_add_f32 v[112:113], v[112:113], v[112:113] op_sel_hi:[0,1]
	v_pk_add_f32 v[114:115], v[114:115], v[114:115] op_sel_hi:[0,1]
	v_pk_fma_f32 v[118:119], v[96:97], v[96:97], v[102:103] op_sel_hi:[1,1,0]
	v_fmamk_f32 v85, v136, 0xb9800000, v85
	v_fmac_f32_e32 v84, 0xb9800000, v136
	v_fmamk_f32 v83, v136, 0xb9800000, v83
	v_fmac_f32_e32 v82, 0xb9800000, v136
	v_mul_f32_e32 v116, v82, v82
	v_mul_f32_e32 v118, v83, v83
	v_mul_f32_e32 v114, v84, v84
	v_mul_f32_e32 v112, v85, v85
	v_pk_add_f32 v[116:117], v[116:117], v[118:119]
	v_pk_add_f32 v[112:113], v[114:115], v[112:113]
	v_fmamk_f32 v87, v136, 0xb9800000, v87
	v_pk_add_f32 v[112:113], v[116:117], v[112:113]
	v_fmac_f32_e32 v86, 0xb9800000, v136
	v_fmamk_f32 v89, v136, 0xb9800000, v89
	v_fmac_f32_e32 v88, 0xb9800000, v136
	v_pk_add_f32 v[128:129], v[112:113], v[112:113] op_sel_hi:[0,1]
	v_pk_mul_f32 v[112:113], v[88:89], v[88:89]
	v_pk_mul_f32 v[114:115], v[86:87], v[86:87]
	v_fmac_f32_e32 v76, 0xb9800000, v136
	v_pk_mov_b32 v[116:117], v[114:115], v[112:113] op_sel:[1,0]
	v_mov_b32_e32 v115, v113
	v_pk_add_f32 v[112:113], v[116:117], v[114:115]
	v_fmamk_f32 v77, v136, 0xb9800000, v77
	v_pk_add_f32 v[130:131], v[112:113], v[112:113] op_sel_hi:[0,1]
	global_load_dwordx4 v[112:115], v[40:41], off
	global_load_dwordx4 v[116:119], v[38:39], off
	global_load_dwordx4 v[120:123], v[38:39], off offset:16
	global_load_dwordx4 v[124:127], v[40:41], off offset:16
	v_fmac_f32_e32 v78, 0xb9800000, v136
	v_mul_f32_e32 v102, v76, v76
	v_fmamk_f32 v79, v136, 0xb9800000, v79
	v_pk_fma_f32 v[132:133], v[76:77], v[76:77], v[102:103] op_sel_hi:[1,1,0]
	v_mul_f32_e32 v102, v78, v78
	v_pk_fma_f32 v[134:135], v[78:79], v[78:79], v[102:103] op_sel_hi:[1,1,0]
	v_fmamk_f32 v69, v136, 0xb9800000, v69
	v_fmac_f32_e32 v68, 0xb9800000, v136
	v_fmamk_f32 v67, v136, 0xb9800000, v67
	v_fmac_f32_e32 v66, 0xb9800000, v136
	v_mul_f32_e32 v132, v66, v66
	v_mul_f32_e32 v134, v67, v67
; __device__ __forceinline__ float wave_sum(float v) {
; #pragma unroll
;     for (int o = 1; o < 64; o <<= 1) v += __shfl_xor(v, o);
;     return v;
; __device__ __forceinline__ void p6_final_ln(const Frame& F) {
;     ...
;         for (int j = 0; j < 16; ++j) { const f32x4 d = z[j] - mean; z[j] = d; q += (d[0] * d[0] + d[1] * d[1]) + (d[2] * d[2] + d[3] * d[3]); }
;         const float rstd = __builtin_amdgcn_rsqf(wave_sum(q) * (1.f / DM) + LN_EPS);
	v_mul_f32_e32 v130, v68, v68
	v_mul_f32_e32 v128, v69, v69
	v_pk_add_f32 v[132:133], v[132:133], v[134:135]
	v_pk_add_f32 v[128:129], v[130:131], v[128:129]
	v_fmamk_f32 v63, v136, 0xb9800000, v63
	v_fmac_f32_e32 v62, 0xb9800000, v136
	v_fmamk_f32 v65, v136, 0xb9800000, v65
	v_fmac_f32_e32 v64, 0xb9800000, v136
	v_pk_add_f32 v[128:129], v[132:133], v[128:129]
	v_pk_mul_f32 v[130:131], v[64:65], v[64:65]
	v_pk_mul_f32 v[132:133], v[62:63], v[62:63]
	v_fmac_f32_e32 v2, 0xb9800000, v136
	v_pk_mov_b32 v[134:135], v[132:133], v[130:131] op_sel:[1,0]
	v_mov_b32_e32 v133, v131
	v_fmamk_f32 v3, v136, 0xb9800000, v3
	v_fmac_f32_e32 v0, 0xb9800000, v136
	v_mul_f32_e32 v102, v2, v2
	v_pk_add_f32 v[130:131], v[134:135], v[132:133]
	v_fmamk_f32 v1, v136, 0xb9800000, v1
	v_pk_fma_f32 v[132:133], v[2:3], v[2:3], v[102:103] op_sel_hi:[1,1,0]
	v_mul_f32_e32 v102, v0, v0
	v_pk_add_f32 v[128:129], v[128:129], v[128:129] op_sel_hi:[0,1]
	v_pk_add_f32 v[130:131], v[130:131], v[130:131] op_sel_hi:[0,1]
	v_pk_fma_f32 v[134:135], v[0:1], v[0:1], v[102:103] op_sel_hi:[1,1,0]
	v_fmamk_f32 v47, v136, 0xb9800000, v47
	v_fmac_f32_e32 v46, 0xb9800000, v136
	v_fmamk_f32 v49, v136, 0xb9800000, v49
	v_fmac_f32_e32 v48, 0xb9800000, v136
	v_mul_f32_e32 v132, v48, v48
	v_mul_f32_e32 v134, v49, v49
	v_mul_f32_e32 v130, v46, v46
	v_mul_f32_e32 v128, v47, v47
	v_pk_add_f32 v[132:133], v[132:133], v[134:135]
	v_pk_add_f32 v[128:129], v[130:131], v[128:129]
	s_nop 0
	v_pk_add_f32 v[128:129], v[132:133], v[128:129]
	s_nop 0
	v_add_f32_e32 v102, v128, v129
	ds_bpermute_b32 v128, v5, v102
	s_waitcnt lgkmcnt(0)
	v_add_f32_e32 v102, v102, v128
	ds_bpermute_b32 v128, v7, v102
	s_waitcnt lgkmcnt(0)
	v_add_f32_e32 v102, v102, v128
	ds_bpermute_b32 v128, v9, v102
	s_waitcnt lgkmcnt(0)
	v_add_f32_e32 v102, v102, v128
	ds_bpermute_b32 v128, v11, v102
	s_waitcnt lgkmcnt(0)
	v_add_f32_e32 v102, v102, v128
	ds_bpermute_b32 v128, v13, v102
	s_waitcnt lgkmcnt(0)
	v_add_f32_e32 v102, v102, v128
	ds_bpermute_b32 v128, v103, v102
	s_waitcnt lgkmcnt(0)
	v_add_f32_e32 v102, v102, v128
	v_fmamk_f32 v102, v102, 0x39800000, v106
	v_rsq_f32_e32 v102, v102
	s_nop 0
	v_pk_mul_f32 v[128:129], v[92:93], v[102:103] op_sel_hi:[1,0]
	v_pk_mul_f32 v[90:91], v[90:91], v[102:103] op_sel_hi:[1,0]
	v_pk_mul_f32 v[70:71], v[70:71], v[102:103] op_sel_hi:[1,0]
	s_waitcnt vmcnt(0)
; __device__ __forceinline__ void p6_final_ln(const Frame& F) {
;     ...
;         float* yr = F.out + (size_t)m * DM;
; #pragma unroll
;         for (int j = 0; j < 8; ++j) { const int col = j * 512 + lane * 8;
;             const f32x4 ga = *(const f32x4*)(F.ln_g + col), gb = *(const f32x4*)(F.ln_g + col + 4), ba = *(const f32x4*)(F.ln_b + col), bb = *(const f32x4*)(F.ln_b + col + 4);
;             *(f32x4*)(yr + col) = z[2 * j] * rstd * ga + ba; *(f32x4*)(yr + col + 4) = z[2 * j + 1] * rstd * gb + bb; }
	v_pk_fma_f32 v[92:93], v[146:147], v[90:91], v[154:155]
	v_pk_fma_f32 v[90:91], v[144:145], v[128:129], v[152:153]
	global_store_dwordx4 v109, v[90:93], s[12:13]
	v_pk_mul_f32 v[60:61], v[60:61], v[102:103] op_sel_hi:[1,0]
	v_pk_mul_f32 v[58:59], v[58:59], v[102:103] op_sel_hi:[1,0]
	v_pk_mul_f32 v[90:91], v[72:73], v[102:103] op_sel_hi:[1,0]
	v_pk_fma_f32 v[72:73], v[142:143], v[70:71], v[150:151]
	v_pk_fma_f32 v[70:71], v[140:141], v[90:91], v[148:149]
	global_store_dwordx4 v109, v[70:73], s[12:13] offset:16
	s_nop 0
	s_nop 0
	s_nop 0
	s_nop 0
	s_nop 0
	v_pk_mul_f32 v[56:57], v[56:57], v[102:103] op_sel_hi:[1,0]
	v_pk_mul_f32 v[54:55], v[54:55], v[102:103] op_sel_hi:[1,0]
	v_pk_mul_f32 v[52:53], v[52:53], v[102:103] op_sel_hi:[1,0]
	v_pk_mul_f32 v[50:51], v[50:51], v[102:103] op_sel_hi:[1,0]
	v_pk_mul_f32 v[44:45], v[44:45], v[102:103] op_sel_hi:[1,0]
	v_pk_mul_f32 v[42:43], v[42:43], v[102:103] op_sel_hi:[1,0]
	v_pk_mul_f32 v[76:77], v[76:77], v[102:103] op_sel_hi:[1,0]
	v_pk_mul_f32 v[68:69], v[68:69], v[102:103] op_sel_hi:[1,0]
	v_pk_mul_f32 v[66:67], v[66:67], v[102:103] op_sel_hi:[1,0]
	v_pk_mul_f32 v[64:65], v[64:65], v[102:103] op_sel_hi:[1,0]
	v_pk_mul_f32 v[62:63], v[62:63], v[102:103] op_sel_hi:[1,0]
	v_pk_mul_f32 v[46:47], v[46:47], v[102:103] op_sel_hi:[1,0]
	v_pk_mul_f32 v[48:49], v[48:49], v[102:103] op_sel_hi:[1,0]
	s_nop 0
	v_pk_fma_f32 v[58:59], v[160:161], v[58:59], v[156:157]
	v_pk_fma_f32 v[60:61], v[162:163], v[60:61], v[158:159]
	s_nop 0
	v_pk_fma_f32 v[54:55], v[164:165], v[54:55], v[168:169]
	v_pk_fma_f32 v[56:57], v[166:167], v[56:57], v[170:171]
	global_store_dwordx4 v109, v[58:61], s[12:13] offset:2048
	global_store_dwordx4 v109, v[54:57], s[12:13] offset:2064
	s_nop 0
	s_nop 0
	s_nop 0
	s_nop 0
	s_nop 0
	s_nop 0
	v_pk_fma_f32 v[50:51], v[176:177], v[50:51], v[172:173]
	v_pk_fma_f32 v[52:53], v[178:179], v[52:53], v[174:175]
	s_nop 0
	v_pk_fma_f32 v[42:43], v[180:181], v[42:43], v[184:185]
	v_pk_fma_f32 v[44:45], v[182:183], v[44:45], v[186:187]
	global_store_dwordx4 v104, v[50:53], s[12:13]
	global_store_dwordx4 v104, v[42:45], s[12:13] offset:16
	s_nop 0
	s_nop 0
	s_nop 0
	s_nop 0
	s_nop 0
	v_pk_mul_f32 v[70:71], v[80:81], v[102:103] op_sel_hi:[1,0]
	v_pk_mul_f32 v[72:73], v[74:75], v[102:103] op_sel_hi:[1,0]
	v_pk_mul_f32 v[74:75], v[84:85], v[102:103] op_sel_hi:[1,0]
	v_pk_mul_f32 v[80:81], v[82:83], v[102:103] op_sel_hi:[1,0]
	s_nop 0
	v_pk_fma_f32 v[42:43], v[192:193], v[72:73], v[188:189]
	v_pk_fma_f32 v[44:45], v[194:195], v[70:71], v[190:191]
	global_store_dwordx4 v105, v[42:45], s[12:13]
	v_pk_mul_f32 v[70:71], v[96:97], v[102:103] op_sel_hi:[1,0]
	v_pk_mul_f32 v[72:73], v[94:95], v[102:103] op_sel_hi:[1,0]
	v_pk_mul_f32 v[44:45], v[100:101], v[102:103] op_sel_hi:[1,0]
	v_pk_mul_f32 v[42:43], v[98:99], v[102:103] op_sel_hi:[1,0]
	s_nop 0
	v_pk_fma_f32 v[44:45], v[198:199], v[44:45], v[202:203]
	v_pk_fma_f32 v[42:43], v[196:197], v[42:43], v[200:201]
	global_store_dwordx4 v105, v[42:45], s[12:13] offset:16
	s_nop 0
	s_nop 0
	s_nop 0
	s_nop 0
	s_nop 0
	s_nop 0
	v_pk_fma_f32 v[42:43], v[208:209], v[72:73], v[204:205]
	v_pk_fma_f32 v[44:45], v[210:211], v[70:71], v[206:207]
	s_nop 0
	v_pk_fma_f32 v[50:51], v[212:213], v[80:81], v[216:217]
	v_pk_fma_f32 v[52:53], v[214:215], v[74:75], v[218:219]
	global_store_dwordx4 v107, v[42:45], s[12:13]
	global_store_dwordx4 v107, v[50:53], s[12:13] offset:16
	s_nop 0
	s_nop 0
	s_nop 0
	s_nop 0
	s_nop 0
	v_pk_mul_f32 v[70:71], v[88:89], v[102:103] op_sel_hi:[1,0]
	v_pk_mul_f32 v[72:73], v[86:87], v[102:103] op_sel_hi:[1,0]
	v_pk_mul_f32 v[74:75], v[78:79], v[102:103] op_sel_hi:[1,0]
	s_nop 0
	v_pk_fma_f32 v[42:43], v[224:225], v[72:73], v[220:221]
	v_pk_fma_f32 v[44:45], v[226:227], v[70:71], v[222:223]
	s_nop 0
	v_pk_fma_f32 v[50:51], v[228:229], v[76:77], v[232:233]
	v_pk_fma_f32 v[52:53], v[230:231], v[74:75], v[234:235]
	global_store_dwordx4 v108, v[42:45], s[12:13]
	global_store_dwordx4 v108, v[50:53], s[12:13] offset:16
	s_nop 0
	s_nop 0
	s_nop 0
	s_nop 0
	s_nop 0
	s_nop 0
	v_pk_fma_f32 v[42:43], v[240:241], v[66:67], v[236:237]
	v_pk_fma_f32 v[44:45], v[242:243], v[68:69], v[238:239]
	s_nop 0
	v_pk_fma_f32 v[50:51], v[244:245], v[62:63], v[248:249]
	v_pk_fma_f32 v[52:53], v[246:247], v[64:65], v[250:251]
	global_store_dwordx4 v111, v[42:45], s[12:13]
	global_store_dwordx4 v111, v[50:53], s[12:13] offset:16
	s_nop 0
	s_nop 0
	s_nop 0
	s_nop 0
	s_nop 0
	v_pk_mul_f32 v[62:63], v[0:1], v[102:103] op_sel_hi:[1,0]
	v_pk_mul_f32 v[0:1], v[2:3], v[102:103] op_sel_hi:[1,0]
	s_nop 0
	v_pk_fma_f32 v[2:3], v[118:119], v[62:63], v[114:115]
	v_pk_fma_f32 v[0:1], v[116:117], v[0:1], v[112:113]
	s_nop 0
	v_pk_fma_f32 v[42:43], v[48:49], v[120:121], v[124:125]
	v_pk_fma_f32 v[44:45], v[46:47], v[122:123], v[126:127]
	global_store_dwordx4 v110, v[0:3], s[12:13]
	global_store_dwordx4 v110, v[42:45], s[12:13] offset:16
	s_cbranch_scc0 .LBB0_578
